# sc1 write-through also on the first norm phase's 8-byte H stores (less dirty L2 at the following grid barrier)
# baseline (speedup 1.0000x reference)
.LBB0_157:
	global_load_dwordx4 v[36:39], v[78:79], off offset:-4096
	global_load_dwordx4 v[32:35], v[78:79], off offset:-3072
	global_load_dwordx4 v[40:43], v[78:79], off offset:-2048
	global_load_dwordx4 v[44:47], v[78:79], off
	global_load_dwordx4 v[48:51], v[78:79], off offset:-1024
	global_load_dwordx4 v[52:55], v[78:79], off offset:1024
	global_load_dwordx4 v[56:59], v[78:79], off offset:3072
	global_load_dwordx4 v[60:63], v[78:79], off offset:2048
	v_lshl_add_u64 v[128:129], v[80:81], 0, s[12:13]
	v_add_co_u32_e32 v128, vcc, s20, v128
	s_add_u32 s12, s12, 0x1000
	s_nop 0
	v_addc_co_u32_e32 v129, vcc, 0, v129, vcc
	s_addc_u32 s13, s13, 0
	v_lshl_add_u64 v[78:79], v[78:79], 0, s[10:11]
	s_cmpk_eq_u32 s12, 0x8000
	s_waitcnt vmcnt(7)
	v_mov_b32_e32 v132, v37
	s_waitcnt vmcnt(6)
	v_mov_b32_e32 v133, v33
	v_mov_b32_e32 v136, v39
	v_mov_b32_e32 v137, v35
	v_mov_b32_e32 v130, v36
	v_mov_b32_e32 v131, v32
	v_mov_b32_e32 v134, v38
	v_mov_b32_e32 v135, v34
	s_waitcnt vmcnt(5)
	v_pk_mul_f32 v[138:139], v[42:43], v[42:43]
	v_pk_mul_f32 v[140:141], v[40:41], v[40:41]
	v_pk_mul_f32 v[132:133], v[132:133], v[132:133]
	v_pk_mul_f32 v[136:137], v[136:137], v[136:137]
	v_pk_mov_b32 v[154:155], v[140:141], v[138:139] op_sel:[1,0]
	v_mov_b32_e32 v141, v139
	v_pk_fma_f32 v[130:131], v[130:131], v[130:131], v[132:133]
	v_pk_fma_f32 v[132:133], v[134:135], v[134:135], v[136:137]
	s_waitcnt vmcnt(3)
	v_mul_f32_e32 v142, v49, v49
	v_mul_f32_e32 v144, v51, v51
	v_pk_add_f32 v[134:135], v[154:155], v[140:141]
	v_pk_add_f32 v[130:131], v[130:131], v[132:133]
	v_mul_f32_e32 v127, v44, v44
	v_mul_f32_e32 v153, v45, v45
	v_mul_f32_e32 v156, v46, v46
	v_mul_f32_e32 v157, v47, v47
	v_pk_fma_f32 v[138:139], v[48:49], v[48:49], v[142:143] op_sel_hi:[1,1,0]
	v_pk_fma_f32 v[142:143], v[50:51], v[50:51], v[144:145] op_sel_hi:[1,1,0]
	v_pk_add_f32 v[132:133], v[134:135], v[134:135] op_sel:[0,1] op_sel_hi:[1,0]
	v_pk_add_f32 v[130:131], v[130:131], v[130:131] op_sel:[0,1] op_sel_hi:[1,0]
	s_waitcnt vmcnt(2)
	v_pk_mul_f32 v[146:147], v[54:55], v[54:55]
	v_pk_mul_f32 v[148:149], v[52:53], v[52:53]
	v_mov_b32_e32 v139, v156
	v_mov_b32_e32 v143, v157
	v_mov_b32_e32 v133, v153
	v_mov_b32_e32 v131, v127
	v_pk_mov_b32 v[144:145], v[148:149], v[146:147] op_sel:[1,0]
	v_mov_b32_e32 v149, v147
	v_pk_add_f32 v[134:135], v[138:139], v[142:143]
	v_pk_add_f32 v[130:131], v[130:131], v[132:133]
	s_waitcnt vmcnt(0)
	v_mul_f32_e32 v150, v61, v61
	v_mul_f32_e32 v152, v63, v63
	v_pk_add_f32 v[136:137], v[144:145], v[148:149]
	v_pk_add_f32 v[130:131], v[130:131], v[134:135]
	v_mul_f32_e32 v158, v56, v56
	v_mul_f32_e32 v159, v57, v57
	v_mul_f32_e32 v160, v58, v58
	v_mul_f32_e32 v161, v59, v59
	v_pk_fma_f32 v[146:147], v[60:61], v[60:61], v[150:151] op_sel_hi:[1,1,0]
	v_pk_fma_f32 v[150:151], v[62:63], v[62:63], v[152:153] op_sel_hi:[1,1,0]
	v_pk_add_f32 v[136:137], v[136:137], v[136:137] op_sel:[0,1] op_sel_hi:[1,0]
	v_pk_add_f32 v[130:131], v[130:131], v[130:131] op_sel:[0,1] op_sel_hi:[1,0]
	v_mov_b32_e32 v147, v160
	v_mov_b32_e32 v151, v161
	v_mov_b32_e32 v137, v159
	v_mov_b32_e32 v131, v158
	v_pk_add_f32 v[138:139], v[146:147], v[150:151]
	v_pk_add_f32 v[130:131], v[130:131], v[136:137]
	s_nop 0
	v_pk_add_f32 v[130:131], v[130:131], v[138:139]
	s_nop 0
	v_add_f32_e32 v127, v130, v131
	ds_bpermute_b32 v130, v114, v127
	s_waitcnt lgkmcnt(0)
	v_add_f32_e32 v127, v127, v130
	ds_bpermute_b32 v130, v115, v127
	s_waitcnt lgkmcnt(0)
	v_add_f32_e32 v127, v127, v130
	ds_bpermute_b32 v130, v116, v127
	s_waitcnt lgkmcnt(0)
	v_add_f32_e32 v127, v127, v130
	ds_bpermute_b32 v130, v117, v127
	s_waitcnt lgkmcnt(0)
	v_add_f32_e32 v127, v127, v130
	ds_bpermute_b32 v130, v118, v127
	s_waitcnt lgkmcnt(0)
	v_add_f32_e32 v127, v127, v130
	ds_bpermute_b32 v130, v119, v127
	s_waitcnt lgkmcnt(0)
	v_add_f32_e32 v127, v127, v130
	v_fmamk_f32 v127, v127, 0x3a000000, v125
	v_mul_f32_e32 v130, 0x4f800000, v127
	v_cmp_gt_f32_e32 vcc, s19, v127
	s_nop 1
	v_cndmask_b32_e32 v127, v127, v130, vcc
	v_sqrt_f32_e32 v130, v127
	s_nop 0
	v_add_u32_e32 v131, -1, v130
	v_add_u32_e32 v132, 1, v130
	v_fma_f32 v133, -v131, v130, v127
	v_fma_f32 v134, -v132, v130, v127
	v_cmp_ge_f32_e64 s[4:5], 0, v133
	s_nop 1
	v_cndmask_b32_e64 v130, v130, v131, s[4:5]
	v_cmp_lt_f32_e64 s[4:5], 0, v134
	s_nop 1
	v_cndmask_b32_e64 v130, v130, v132, s[4:5]
	v_mul_f32_e32 v131, 0x37800000, v130
	v_cndmask_b32_e32 v130, v130, v131, vcc
	v_cmp_class_f32_e32 vcc, v127, v126
	s_nop 1
	v_cndmask_b32_e32 v127, v130, v127, vcc
	v_div_scale_f32 v130, s[4:5], v127, v127, 1.0
	v_rcp_f32_e32 v132, v130
	v_div_scale_f32 v131, vcc, 1.0, v127, 1.0
	v_fma_f32 v133, -v130, v132, 1.0
	v_fmac_f32_e32 v132, v133, v132
	v_mul_f32_e32 v133, v131, v132
	v_fma_f32 v134, -v130, v133, v131
	v_fmac_f32_e32 v133, v134, v132
	v_fma_f32 v130, -v130, v133, v131
	v_div_fmas_f32 v130, v130, v132, v133
	v_div_fixup_f32 v130, v130, v127, 1.0
	v_pk_mul_f32 v[36:37], v[36:37], v[130:131] op_sel_hi:[1,0]
	v_pk_mul_f32 v[32:33], v[32:33], v[130:131] op_sel_hi:[1,0]
	v_pk_mul_f32 v[38:39], v[38:39], v[130:131] op_sel_hi:[1,0]
	v_pk_mul_f32 v[34:35], v[34:35], v[130:131] op_sel_hi:[1,0]
	v_pk_fma_f32 v[36:37], v[84:85], v[36:37], v[0:1]
	v_pk_fma_f32 v[32:33], v[88:89], v[32:33], v[4:5]
	v_pk_mul_f32 v[40:41], v[40:41], v[130:131] op_sel_hi:[1,0]
	v_pk_mul_f32 v[42:43], v[42:43], v[130:131] op_sel_hi:[1,0]
	v_pk_fma_f32 v[38:39], v[82:83], v[38:39], v[2:3]
	v_pk_fma_f32 v[34:35], v[86:87], v[34:35], v[6:7]
	v_cvt_pk_bf16_f32 v36, v36, v37
	v_cvt_pk_bf16_f32 v37, v38, v39
	global_store_dwordx2 v[128:129], v[36:37], off sc1
	v_cvt_pk_bf16_f32 v32, v32, v33
	v_cvt_pk_bf16_f32 v33, v34, v35
	v_pk_mul_f32 v[48:49], v[48:49], v[130:131] op_sel_hi:[1,0]
	v_pk_mul_f32 v[50:51], v[50:51], v[130:131] op_sel_hi:[1,0]
	v_pk_fma_f32 v[42:43], v[90:91], v[42:43], v[10:11]
	v_pk_fma_f32 v[40:41], v[92:93], v[40:41], v[8:9]
	global_store_dwordx2 v[128:129], v[32:33], off offset:512 sc1
	v_cvt_pk_bf16_f32 v32, v40, v41
	v_cvt_pk_bf16_f32 v33, v42, v43
	v_pk_mul_f32 v[44:45], v[44:45], v[130:131] op_sel_hi:[1,0]
	v_pk_mul_f32 v[46:47], v[46:47], v[130:131] op_sel_hi:[1,0]
	v_pk_fma_f32 v[50:51], v[94:95], v[50:51], v[14:15]
	v_pk_fma_f32 v[48:49], v[96:97], v[48:49], v[12:13]
	global_store_dwordx2 v[128:129], v[32:33], off offset:1024 sc1
	v_cvt_pk_bf16_f32 v32, v48, v49
	v_cvt_pk_bf16_f32 v33, v50, v51
	v_pk_mul_f32 v[52:53], v[52:53], v[130:131] op_sel_hi:[1,0]
	v_pk_mul_f32 v[54:55], v[54:55], v[130:131] op_sel_hi:[1,0]
	v_pk_fma_f32 v[46:47], v[98:99], v[46:47], v[18:19]
	v_pk_fma_f32 v[44:45], v[100:101], v[44:45], v[16:17]
	global_store_dwordx2 v[128:129], v[32:33], off offset:1536 sc1
	v_cvt_pk_bf16_f32 v32, v44, v45
	v_cvt_pk_bf16_f32 v33, v46, v47
	v_pk_mul_f32 v[60:61], v[60:61], v[130:131] op_sel_hi:[1,0]
	v_pk_mul_f32 v[62:63], v[62:63], v[130:131] op_sel_hi:[1,0]
	v_pk_fma_f32 v[54:55], v[102:103], v[54:55], v[22:23]
	v_pk_fma_f32 v[52:53], v[104:105], v[52:53], v[20:21]
	global_store_dwordx2 v[128:129], v[32:33], off offset:2048 sc1
	v_cvt_pk_bf16_f32 v32, v52, v53
	v_cvt_pk_bf16_f32 v33, v54, v55
	v_pk_mul_f32 v[56:57], v[56:57], v[130:131] op_sel_hi:[1,0]
	v_pk_mul_f32 v[58:59], v[58:59], v[130:131] op_sel_hi:[1,0]
	v_pk_fma_f32 v[62:63], v[106:107], v[62:63], v[26:27]
	v_pk_fma_f32 v[60:61], v[108:109], v[60:61], v[24:25]
	global_store_dwordx2 v[128:129], v[32:33], off offset:2560 sc1
	v_cvt_pk_bf16_f32 v32, v60, v61
	v_cvt_pk_bf16_f32 v33, v62, v63
	v_pk_fma_f32 v[58:59], v[110:111], v[58:59], v[30:31]
	v_pk_fma_f32 v[56:57], v[112:113], v[56:57], v[28:29]
	global_store_dwordx2 v[128:129], v[32:33], off offset:3072 sc1
	v_cvt_pk_bf16_f32 v32, v56, v57
	v_cvt_pk_bf16_f32 v33, v58, v59
	global_store_dwordx2 v[128:129], v[32:33], off offset:3584 sc1
	s_cbranch_scc0 .LBB0_157
	s_add_i32 s0, s0, s1
	s_add_i32 s8, s8, s18
	s_cmpk_gt_i32 s0, 0x7ff
	s_cbranch_scc0 .LBB0_156
